# attention loop: rescale factor computed only on the rescale path (alpha is exactly 1 when the wave-uniform under-threshold flag is set); rescale branch tests the scalar flag
# speedup vs baseline: 1.0085x; 1.0024x over previous
; __device__ __forceinline__ void finishSM(f32x16& p0, f32x16& p1, float alpha, float& l_reg, bf16x8& pa0, bf16x8& pa1, bf16x8& pa2, bf16x8& pa3) {
; #pragma unroll
;     for (int r = 0; r < 16; ++r) p1[r] = __builtin_amdgcn_exp2f(p1[r]);
;     float ps = 0;
; #pragma unroll
;     for (int r = 0; r < 16; ++r) ps += p0[r];
; #pragma unroll
;     for (int r = 0; r < 16; ++r) ps += p1[r];
;     { auto rr = __builtin_amdgcn_permlane32_swap(__float_as_uint(ps), __float_as_uint(ps), false, false);
;       ps = __uint_as_float(rr[0]) + __uint_as_float(rr[1]); }
;     l_reg = l_reg * alpha + ps;
;     ...
;     PK4(p0, 0, pa0); PK4(p0, 8, pa1); PK4(p1, 0, pa2); PK4(p1, 8, pa3);
;     ...
; }
; template <int KB>
; __device__ __forceinline__ void qkt(f32x16& p0, f32x16& p1, const char* K_lds, int r32, int hi, const bf16x8* qr) {
;     p0 = f32x16{}; p1 = f32x16{};
;     const char* kb[4];
; #pragma unroll
;     for (int dd = 0; dd < 4; ++dd) kb[dd] = K_lds + KB * SHM_K + KSWZ(r32, (dd * 16 + hi * 8) * 2);
; #pragma unroll
;     for (int d0 = 0; d0 < 8; ++d0) { const char* a = kb[d0 & 3] + (d0 >> 2) * 128;
;         bf16x8 b0 = *reinterpret_cast<const bf16x8*>(a);
;         bf16x8 b1 = *reinterpret_cast<const bf16x8*>(a + 32 * 256);
;         p0 = __builtin_amdgcn_mfma_f32_32x32x16_bf16(b0, qr[d0], p0, 0, 0, 0);
;         p1 = __builtin_amdgcn_mfma_f32_32x32x16_bf16(b1, qr[d0], p1, 0, 0, 0); }
; }
; template <int VB>
; __device__ __forceinline__ void pv_tile(f32x16* o, int vb0, bf16x8 pa0, bf16x8 pa1, bf16x8 pa2, bf16x8 pa3) {
;     ...
;     PV_D0(0); PV_D0(1); PV_D0(2); PV_D0(3);
;     ...
; }
.LBB0_1299:
	global_load_dwordx2 v[146:147], v179, s[68:69] offset:-8
	s_add_u32 s98, s16, 0x40000
	s_addc_u32 s99, s17, 0
	global_load_dwordx4 v[130:133], v188, s[98:99]
	s_add_u32 s98, s16, 0x50000
	s_addc_u32 s99, s17, 0
	global_load_dwordx4 v[134:137], v188, s[98:99]
	s_add_u32 s98, s100, 0x40000
	s_addc_u32 s99, s101, 0
	global_load_dwordx4 v[138:141], v188, s[98:99]
	s_add_u32 s98, s100, 0x50000
	s_addc_u32 s99, s101, 0
	global_load_dwordx4 v[142:145], v188, s[98:99]
	ds_read_b128 v[66:69], v199 offset:49152
	ds_read_b128 v[82:85], v199 offset:57344
	ds_read_b128 v[172:175], v200 offset:49152
	ds_read_b128 v[232:235], v200 offset:57344
	ds_read_b128 v[236:239], v201 offset:49152
	ds_read_b128 v[240:243], v201 offset:57344
	ds_read_b128 v[244:247], v202 offset:49152
	v_exp_f32_e32 v209, v150
	v_add_f32_e32 v150, v220, v219
	v_add_f32_e32 v150, v221, v150
	s_waitcnt lgkmcnt(6)
	v_mfma_f32_32x32x16_bf16 v[66:81], v[66:69], v[126:129], 0
	v_add_f32_e32 v150, v222, v150
	v_add_f32_e32 v150, v223, v150
	v_add_f32_e32 v150, v225, v150
	v_add_f32_e32 v150, v224, v150
	v_add_f32_e32 v150, v226, v150
	s_waitcnt lgkmcnt(5)
	v_mfma_f32_32x32x16_bf16 v[82:97], v[82:85], v[126:129], 0
	v_add_f32_e32 v150, v211, v150
	v_add_f32_e32 v150, v212, v150
	v_exp_f32_e32 v194, v194
	s_waitcnt lgkmcnt(4)
	v_mfma_f32_32x32x16_bf16 v[66:81], v[172:175], v[122:125], v[66:81]
	ds_read_b128 v[172:175], v202 offset:57344
	v_exp_f32_e32 v195, v195
	v_exp_f32_e32 v192, v192
	v_exp_f32_e32 v193, v193
	s_waitcnt lgkmcnt(4)
	v_mfma_f32_32x32x16_bf16 v[82:97], v[232:235], v[122:125], v[82:97]
	ds_read_b128 v[232:235], v199 offset:49280
	v_exp_f32_e32 v158, v158
	v_exp_f32_e32 v159, v159
	s_waitcnt lgkmcnt(4)
	v_mfma_f32_32x32x16_bf16 v[66:81], v[236:239], v[118:121], v[66:81]
	ds_read_b128 v[236:239], v199 offset:57472
	v_exp_f32_e32 v207, v154
	v_exp_f32_e32 v208, v155
	v_exp_f32_e32 v210, v151
	s_waitcnt lgkmcnt(4)
	v_mfma_f32_32x32x16_bf16 v[82:97], v[240:243], v[118:121], v[82:97]
	ds_read_b128 v[240:243], v200 offset:49280
	v_exp_f32_e32 v160, v160
	v_exp_f32_e32 v161, v161
	s_waitcnt lgkmcnt(4)
	v_mfma_f32_32x32x16_bf16 v[66:81], v[244:247], v[114:117], v[66:81]
	ds_read_b128 v[244:247], v200 offset:57472
	v_exp_f32_e32 v227, v156
	v_cvt_pk_bf16_f32 v151, v224, v226
	v_cvt_pk_bf16_f32 v154, v214, v216
	v_cvt_pk_bf16_f32 v155, v217, v218
	v_cvt_pk_bf16_f32 v156, v194, v195
	s_waitcnt lgkmcnt(4)
	v_mfma_f32_32x32x16_bf16 v[82:97], v[172:175], v[114:117], v[82:97]
	ds_read_b128 v[172:175], v201 offset:49280
	v_exp_f32_e32 v228, v157
	v_exp_f32_e32 v229, v152
	s_waitcnt lgkmcnt(4)
	v_mfma_f32_32x32x16_bf16 v[66:81], v[232:235], v[110:113], v[66:81]
	ds_read_b128 v[232:235], v201 offset:57472
	v_exp_f32_e32 v230, v153
	v_cvt_pk_bf16_f32 v152, v211, v212
	v_cvt_pk_bf16_f32 v153, v213, v215
	v_cvt_pk_bf16_f32 v157, v192, v193
	v_cvt_pk_bf16_f32 v211, v229, v230
	s_waitcnt lgkmcnt(4)
	v_mfma_f32_32x32x16_bf16 v[82:97], v[236:239], v[110:113], v[82:97]
	ds_read_b128 v[236:239], v202 offset:49280
	v_add_f32_e32 v249, v213, v150
	v_add_f32_e32 v249, v215, v249
	v_add_f32_e32 v249, v214, v249
	s_waitcnt lgkmcnt(4)
	v_mfma_f32_32x32x16_bf16 v[66:81], v[240:243], v[106:109], v[66:81]
	ds_read_b128 v[240:243], v202 offset:57472
	v_add_f32_e32 v249, v216, v249
	v_add_f32_e32 v249, v217, v249
	v_add_f32_e32 v249, v218, v249
	v_add_f32_e32 v249, v194, v249
	v_add_f32_e32 v248, v195, v249
	s_waitcnt lgkmcnt(4)
	v_mfma_f32_32x32x16_bf16 v[82:97], v[244:247], v[106:109], v[82:97]
	v_add_f32_e32 v248, v192, v248
	v_add_f32_e32 v248, v193, v248
	v_add_f32_e32 v248, v158, v248
	v_add_f32_e32 v248, v159, v248
	v_add_f32_e32 v248, v207, v248
	s_waitcnt lgkmcnt(3)
	v_mfma_f32_32x32x16_bf16 v[66:81], v[172:175], v[102:105], v[66:81]
	v_add_f32_e32 v248, v208, v248
	v_add_f32_e32 v248, v209, v248
	v_add_f32_e32 v248, v210, v248
	v_add_f32_e32 v248, v160, v248
	v_add_f32_e32 v248, v161, v248
	s_waitcnt lgkmcnt(2)
	v_mfma_f32_32x32x16_bf16 v[82:97], v[232:235], v[102:105], v[82:97]
	v_add_f32_e32 v248, v227, v248
	v_add_f32_e32 v248, v228, v248
	v_add_f32_e32 v248, v229, v248
	v_add_f32_e32 v181, v230, v248
	s_waitcnt lgkmcnt(1)
	v_mfma_f32_32x32x16_bf16 v[66:81], v[236:239], v[98:101], v[66:81]
	v_cvt_pk_bf16_f32 v148, v219, v220
	v_cvt_pk_bf16_f32 v149, v221, v222
	v_cvt_pk_bf16_f32 v150, v223, v225
	v_cvt_pk_bf16_f32 v158, v158, v159
	v_cvt_pk_bf16_f32 v159, v207, v208
	s_waitcnt lgkmcnt(0)
	v_mfma_f32_32x32x16_bf16 v[82:97], v[240:243], v[98:101], v[82:97]
	v_cvt_pk_bf16_f32 v208, v209, v210
	v_cvt_pk_bf16_f32 v210, v227, v228
	v_cvt_pk_bf16_f32 v209, v160, v161
	ds_read_b64_tr_b16 v[172:173], v1 offset:0x0
	ds_read_b64_tr_b16 v[174:175], v1 offset:0x800
	ds_read_b64_tr_b16 v[212:213], v1 offset:0x200
	ds_read_b64_tr_b16 v[214:215], v1 offset:0xa00
	ds_read_b64_tr_b16 v[216:217], v1 offset:0x400
	ds_read_b64_tr_b16 v[218:219], v1 offset:0xc00
	ds_read_b64_tr_b16 v[220:221], v1 offset:0x600
	ds_read_b64_tr_b16 v[222:223], v1 offset:0xe00
	ds_read_b64_tr_b16 v[224:225], v1 offset:0x1000
	ds_read_b64_tr_b16 v[226:227], v1 offset:0x1800
	ds_read_b64_tr_b16 v[232:233], v1 offset:0x1200
	ds_read_b64_tr_b16 v[234:235], v1 offset:0x1a00
	ds_read_b64_tr_b16 v[236:237], v1 offset:0x1400
	ds_read_b64_tr_b16 v[238:239], v1 offset:0x1c00
	s_nop 0
	s_waitcnt lgkmcnt(12)
	v_mfma_f32_32x32x16_bf16 v[2:17], v[148:151], v[172:175], v[2:17]
	ds_read_b64_tr_b16 v[240:241], v1 offset:0x1600
	ds_read_b64_tr_b16 v[242:243], v1 offset:0x1e00
	s_waitcnt vmcnt(4)
	v_lshrrev_b32_e32 v160, v163, v146
	v_lshrrev_b32_e32 v161, v163, v147
	v_bfe_i32 v146, v160, 0, 1
	v_bfe_i32 v147, v161, 0, 1
	v_bitop3_b32 v146, v66, s74, v146 bitop3:0xe4
	v_bitop3_b32 v66, v82, s74, v147 bitop3:0xe4
	s_waitcnt lgkmcnt(12)
; __device__ __forceinline__ void sel_mask_tile(f32x16& p0, f32x16& p1, unsigned wlo, unsigned whi, int hi) {
;     const unsigned NEGB = 0xff800000u;
;     const unsigned lo = wlo >> (4 * hi), h2 = whi >> (4 * hi);
; #pragma unroll
;     for (int r = 0; r < 16; ++r) {
;         const int c = (r & 3) + 8 * (r >> 2);
;         const unsigned m0 = (unsigned)__builtin_amdgcn_sbfe((int)lo, c, 1), m1 = (unsigned)__builtin_amdgcn_sbfe((int)h2, c, 1);
;         p0[r] = __uint_as_float((__float_as_uint(p0[r]) & m0) | (NEGB & ~m0));
;         p1[r] = __uint_as_float((__float_as_uint(p1[r]) & m1) | (NEGB & ~m1));
;     }
; }
; __device__ __forceinline__ void partialSM(f32x16& p0, f32x16& p1, float& m_reg, float& mn, float& alpha) {
;     float pmax = p0[0];
; #pragma unroll
;     for (int r = 1; r < 16; ++r) pmax = fmaxf(pmax, p0[r]);
; #pragma unroll
;     for (int r = 0; r < 16; ++r) pmax = fmaxf(pmax, p1[r]);
;     { auto rr = __builtin_amdgcn_permlane32_swap(__float_as_uint(pmax), __float_as_uint(pmax), false, false);
;       pmax = fmaxf(__uint_as_float(rr[0]), __uint_as_float(rr[1])); }
;     constexpr float C2 = 1.4426950408889634f * SCALE;
;     if (__builtin_expect(__all((pmax - m_reg) * SCALE <= THR), 1)) { mn = m_reg; alpha = 1.f; }
;     else { mn = fmaxf(m_reg, pmax); alpha = __builtin_amdgcn_exp2f((m_reg - mn) * C2); m_reg = mn; }
;     const float mnL = -mn * C2;
; #pragma unroll
;     for (int r = 0; r < 16; ++r) p0[r] = fmaf(p0[r], C2, mnL);
; #pragma unroll
;     for (int r = 0; r < 16; ++r) p1[r] = fmaf(p1[r], C2, mnL);
; #pragma unroll
;     for (int r = 0; r < 16; ++r) p0[r] = __builtin_amdgcn_exp2f(p0[r]);
; }
; template <int VB>
; __device__ __forceinline__ void pv_tile(f32x16* o, int vb0, bf16x8 pa0, bf16x8 pa1, bf16x8 pa2, bf16x8 pa3) {
;     ...
;     PV_D0(0); PV_D0(1); PV_D0(2); PV_D0(3);
;     ...
; }
	v_mfma_f32_32x32x16_bf16 v[50:65], v[148:151], v[212:215], v[50:65]
	ds_read_b64_tr_b16 v[244:245], v1 offset:0x2000
	ds_read_b64_tr_b16 v[246:247], v1 offset:0x2800
	v_bfe_i32 v82, v160, 1, 1
	v_bfe_i32 v147, v161, 1, 1
	v_bitop3_b32 v82, v67, s74, v82 bitop3:0xe4
	v_bitop3_b32 v67, v83, s74, v147 bitop3:0xe4
	v_bfe_i32 v83, v160, 2, 1
	v_bfe_i32 v147, v161, 2, 1
	s_waitcnt lgkmcnt(12)
	v_mfma_f32_32x32x16_bf16 v[34:49], v[148:151], v[216:219], v[34:49]
	ds_read_b64_tr_b16 v[248:249], v1 offset:0x2200
	ds_read_b64_tr_b16 v[250:251], v1 offset:0x2a00
	v_bitop3_b32 v83, v68, s74, v83 bitop3:0xe4
	v_bitop3_b32 v68, v84, s74, v147 bitop3:0xe4
	v_bfe_i32 v84, v160, 3, 1
	s_waitcnt lgkmcnt(12)
	v_mfma_f32_32x32x16_bf16 v[18:33], v[148:151], v[220:223], v[18:33]
	ds_read_b64_tr_b16 v[220:221], v1 offset:0x2400
	ds_read_b64_tr_b16 v[222:223], v1 offset:0x2c00
	v_bfe_i32 v148, v161, 3, 1
	v_bitop3_b32 v147, v69, s74, v84 bitop3:0xe4
	v_bfe_i32 v84, v160, 8, 1
	v_bitop3_b32 v69, v85, s74, v148 bitop3:0xe4
	v_bfe_i32 v85, v161, 8, 1
	v_bitop3_b32 v148, v70, s74, v84 bitop3:0xe4
	v_bfe_i32 v84, v160, 9, 1
	s_waitcnt lgkmcnt(12)
	v_mfma_f32_32x32x16_bf16 v[2:17], v[152:155], v[224:227], v[2:17]
	ds_read_b64_tr_b16 v[224:225], v1 offset:0x2600
	ds_read_b64_tr_b16 v[226:227], v1 offset:0x2e00
	v_bitop3_b32 v70, v86, s74, v85 bitop3:0xe4
	v_bfe_i32 v85, v161, 9, 1
	v_bitop3_b32 v149, v71, s74, v84 bitop3:0xe4
	v_bfe_i32 v84, v160, 10, 1
	v_bitop3_b32 v71, v87, s74, v85 bitop3:0xe4
	v_bfe_i32 v85, v161, 10, 1
	s_waitcnt lgkmcnt(12)
	v_mfma_f32_32x32x16_bf16 v[50:65], v[152:155], v[232:235], v[50:65]
	ds_read_b64_tr_b16 v[232:233], v1 offset:0x3000
	ds_read_b64_tr_b16 v[234:235], v1 offset:0x3800
	v_bitop3_b32 v87, v72, s74, v84 bitop3:0xe4
	v_bfe_i32 v84, v160, 11, 1
	v_bitop3_b32 v72, v88, s74, v85 bitop3:0xe4
	v_bfe_i32 v85, v161, 11, 1
	v_bitop3_b32 v88, v73, s74, v84 bitop3:0xe4
	v_bfe_i32 v73, v160, 16, 1
	v_bitop3_b32 v84, v89, s74, v85 bitop3:0xe4
	s_waitcnt lgkmcnt(12)
	v_mfma_f32_32x32x16_bf16 v[34:49], v[152:155], v[236:239], v[34:49]
	ds_read_b64_tr_b16 v[236:237], v1 offset:0x3200
	ds_read_b64_tr_b16 v[238:239], v1 offset:0x3a00
	v_bfe_i32 v85, v161, 16, 1
	v_bitop3_b32 v89, v74, s74, v73 bitop3:0xe4
	v_bfe_i32 v73, v160, 17, 1
	v_bfe_i32 v74, v161, 17, 1
	v_bitop3_b32 v85, v90, s74, v85 bitop3:0xe4
	v_bitop3_b32 v90, v75, s74, v73 bitop3:0xe4
	s_waitcnt lgkmcnt(12)
	v_mfma_f32_32x32x16_bf16 v[18:33], v[152:155], v[240:243], v[18:33]
	ds_read_b64_tr_b16 v[240:241], v1 offset:0x3400
	ds_read_b64_tr_b16 v[242:243], v1 offset:0x3c00
	v_bitop3_b32 v86, v91, s74, v74 bitop3:0xe4
	v_bfe_i32 v73, v160, 18, 1
	v_bfe_i32 v74, v161, 18, 1
	v_bitop3_b32 v91, v76, s74, v73 bitop3:0xe4
	v_bitop3_b32 v76, v92, s74, v74 bitop3:0xe4
	v_bfe_i32 v73, v160, 19, 1
	v_bfe_i32 v74, v161, 19, 1
	s_waitcnt lgkmcnt(12)
	v_mfma_f32_32x32x16_bf16 v[2:17], v[156:159], v[244:247], v[2:17]
	ds_read_b64_tr_b16 v[244:245], v1 offset:0x3600
	ds_read_b64_tr_b16 v[246:247], v1 offset:0x3e00
	v_bitop3_b32 v92, v77, s74, v73 bitop3:0xe4
	v_bitop3_b32 v77, v93, s74, v74 bitop3:0xe4
	v_bfe_i32 v73, v160, 24, 1
	v_bfe_i32 v74, v161, 24, 1
	v_bitop3_b32 v93, v78, s74, v73 bitop3:0xe4
	v_bitop3_b32 v78, v94, s74, v74 bitop3:0xe4
	s_waitcnt lgkmcnt(12)
	v_mfma_f32_32x32x16_bf16 v[50:65], v[156:159], v[248:251], v[50:65]
	v_bfe_i32 v73, v160, 25, 1
	v_bfe_i32 v74, v161, 25, 1
	v_bitop3_b32 v79, v79, s74, v73 bitop3:0xe4
	v_bitop3_b32 v73, v95, s74, v74 bitop3:0xe4
	v_bfe_i32 v74, v160, 26, 1
	v_bfe_i32 v75, v161, 26, 1
	v_bitop3_b32 v80, v80, s74, v74 bitop3:0xe4
	s_waitcnt lgkmcnt(10)
	v_mfma_f32_32x32x16_bf16 v[34:49], v[156:159], v[220:223], v[34:49]
	v_bitop3_b32 v74, v96, s74, v75 bitop3:0xe4
	v_bfe_i32 v75, v160, 27, 1
	v_bfe_i32 v94, v161, 27, 1
	v_bitop3_b32 v81, v81, s74, v75 bitop3:0xe4
	v_bitop3_b32 v75, v97, s74, v94 bitop3:0xe4
	s_waitcnt lgkmcnt(8)
	v_mfma_f32_32x32x16_bf16 v[18:33], v[156:159], v[224:227], v[18:33]
	v_max_f32_e32 v94, v146, v82
	v_max3_f32 v94, v94, v83, v147
	v_max3_f32 v94, v94, v148, v149
	v_max3_f32 v94, v94, v87, v88
	v_max3_f32 v94, v94, v89, v90
	v_max3_f32 v94, v94, v91, v92
	s_waitcnt lgkmcnt(6)
	v_mfma_f32_32x32x16_bf16 v[2:17], v[208:211], v[232:235], v[2:17]
	v_max3_f32 v94, v94, v93, v79
	v_max3_f32 v94, v94, v80, v81
	v_max3_f32 v94, v94, v66, v67
	v_max3_f32 v94, v94, v68, v69
	v_max3_f32 v94, v94, v70, v71
	v_max3_f32 v94, v94, v72, v84
	s_waitcnt lgkmcnt(4)
	v_mfma_f32_32x32x16_bf16 v[50:65], v[208:211], v[236:239], v[50:65]
	v_max3_f32 v94, v94, v85, v86
	v_max3_f32 v94, v94, v76, v77
	v_max3_f32 v94, v94, v78, v73
	v_max3_f32 v94, v94, v74, v75
	v_mov_b32_e32 v95, v94
	s_nop 1
	v_permlane32_swap_b32_e32 v94, v95
	s_waitcnt lgkmcnt(2)
	v_mfma_f32_32x32x16_bf16 v[34:49], v[208:211], v[240:243], v[34:49]
	v_max_f32_e32 v94, v94, v95
	v_sub_f32_e32 v95, v94, v206
	s_waitcnt lgkmcnt(0)
	v_mfma_f32_32x32x16_bf16 v[18:33], v[208:211], v[244:247], v[18:33]
	v_mul_f32_e32 v95, 0x3db504f3, v95
	v_cmp_ge_f32_e32 vcc, s75, v95
	s_waitcnt vmcnt(0)
	ds_write_b128 v204, v[138:141] offset:32768
	ds_write_b128 v204, v[142:145] offset:40960
	s_cmp_eq_u64 vcc, exec
	s_cselect_b64 s[6:7], -1, 0
	s_cbranch_scc1 .Lp5_b1fast
	v_max_f32_e32 v94, v206, v94
	v_sub_f32_e32 v96, v206, v94
	v_mul_f32_e32 v96, 0x3e0293ee, v96
	v_exp_f32_e32 v96, v96
.Lp5_b1fast:
	s_barrier
	s_waitcnt vmcnt(0)
	v_cndmask_b32_e64 v208, v96, 1.0, s[6:7]
	s_not_b64 vcc, s[6:7]
	ds_write_b128 v197, v[130:133]
	ds_write_b128 v198, v[134:137]
	s_cbranch_vccz .LBB0_1303
	s_and_saveexec_b64 s[36:37], s[0:1]
	ds_write_b32 v185, v208 offset:128
	s_or_b64 exec, exec, s[36:37]
	s_waitcnt lgkmcnt(0)
	ds_read_b128 v[150:153], v183 offset:224
	ds_read_b128 v[154:157], v183 offset:192
	ds_read_b128 v[158:161], v183 offset:160
	ds_read_b128 v[172:175], v183 offset:128
	s_waitcnt lgkmcnt(3)
	v_pk_mul_f32 v[16:17], v[16:17], v[152:153]
	s_waitcnt lgkmcnt(2)
	v_pk_mul_f32 v[12:13], v[12:13], v[156:157]
	s_waitcnt lgkmcnt(1)
	v_pk_mul_f32 v[8:9], v[8:9], v[160:161]
	s_waitcnt lgkmcnt(0)
	v_pk_mul_f32 v[4:5], v[4:5], v[174:175]
	v_pk_mul_f32 v[14:15], v[14:15], v[150:151]
	v_pk_mul_f32 v[10:11], v[10:11], v[154:155]
	v_pk_mul_f32 v[6:7], v[6:7], v[158:159]
	v_pk_mul_f32 v[2:3], v[2:3], v[172:173]
	v_pk_mul_f32 v[64:65], v[64:65], v[152:153]
	v_pk_mul_f32 v[60:61], v[60:61], v[156:157]
	v_pk_mul_f32 v[56:57], v[56:57], v[160:161]
	v_pk_mul_f32 v[52:53], v[52:53], v[174:175]
	v_pk_mul_f32 v[62:63], v[62:63], v[150:151]
	v_pk_mul_f32 v[58:59], v[58:59], v[154:155]
	v_pk_mul_f32 v[54:55], v[54:55], v[158:159]
	v_pk_mul_f32 v[50:51], v[50:51], v[172:173]
	v_pk_mul_f32 v[48:49], v[48:49], v[152:153]
	v_pk_mul_f32 v[44:45], v[44:45], v[156:157]
	v_pk_mul_f32 v[40:41], v[40:41], v[160:161]
	v_pk_mul_f32 v[36:37], v[36:37], v[174:175]
	v_pk_mul_f32 v[46:47], v[46:47], v[150:151]
	v_pk_mul_f32 v[42:43], v[42:43], v[154:155]
	v_pk_mul_f32 v[38:39], v[38:39], v[158:159]
	v_pk_mul_f32 v[34:35], v[34:35], v[172:173]
	v_pk_mul_f32 v[32:33], v[32:33], v[152:153]
	v_pk_mul_f32 v[28:29], v[28:29], v[156:157]
	v_pk_mul_f32 v[24:25], v[24:25], v[160:161]
	v_pk_mul_f32 v[20:21], v[20:21], v[174:175]
	v_pk_mul_f32 v[30:31], v[30:31], v[150:151]
	v_pk_mul_f32 v[26:27], v[26:27], v[154:155]
	v_pk_mul_f32 v[22:23], v[22:23], v[158:159]
	v_pk_mul_f32 v[18:19], v[18:19], v[172:173]

; __device__ __forceinline__ void partialSM(f32x16& p0, f32x16& p1, float& m_reg, float& mn, float& alpha) {
;     ...
;     if (__builtin_expect(__all((pmax - m_reg) * SCALE <= THR), 1)) { mn = m_reg; alpha = 1.f; }
;     else { mn = fmaxf(m_reg, pmax); alpha = __builtin_amdgcn_exp2f((m_reg - mn) * C2); m_reg = mn; }
.LBB0_1307:
	v_mov_b32_e32 v207, 1.0
	s_not_b64 vcc, s[6:7]
	s_cbranch_vccz .LBB0_1311
	v_max_f32_e32 v76, v206, v76
	v_sub_f32_e32 v77, v206, v76
	v_mul_f32_e32 v77, 0x3e0293ee, v77
	v_exp_f32_e32 v77, v77
	s_nop 0
	v_cndmask_b32_e64 v207, v77, 1.0, s[6:7]
	s_and_saveexec_b64 s[36:37], s[0:1]
	ds_write_b32 v185, v207 offset:128
	s_or_b64 exec, exec, s[36:37]
	s_waitcnt lgkmcnt(0)
	ds_read_b128 v[78:81], v183 offset:224
	ds_read_b128 v[130:133], v183 offset:192
	ds_read_b128 v[134:137], v183 offset:160
	ds_read_b128 v[138:141], v183 offset:128
	s_waitcnt lgkmcnt(3)
	v_pk_mul_f32 v[16:17], v[16:17], v[80:81]
	s_waitcnt lgkmcnt(2)
	v_pk_mul_f32 v[12:13], v[12:13], v[132:133]
	s_waitcnt lgkmcnt(1)
	v_pk_mul_f32 v[8:9], v[8:9], v[136:137]
	s_waitcnt lgkmcnt(0)
	v_pk_mul_f32 v[4:5], v[4:5], v[140:141]
	v_pk_mul_f32 v[14:15], v[14:15], v[78:79]
	v_pk_mul_f32 v[10:11], v[10:11], v[130:131]
	v_pk_mul_f32 v[6:7], v[6:7], v[134:135]
	v_pk_mul_f32 v[2:3], v[2:3], v[138:139]
	v_pk_mul_f32 v[64:65], v[64:65], v[80:81]
	v_pk_mul_f32 v[60:61], v[60:61], v[132:133]
	v_pk_mul_f32 v[56:57], v[56:57], v[136:137]
	v_pk_mul_f32 v[52:53], v[52:53], v[140:141]
	v_pk_mul_f32 v[62:63], v[62:63], v[78:79]
	v_pk_mul_f32 v[58:59], v[58:59], v[130:131]
	v_pk_mul_f32 v[54:55], v[54:55], v[134:135]
	v_pk_mul_f32 v[50:51], v[50:51], v[138:139]
	v_pk_mul_f32 v[48:49], v[48:49], v[80:81]
	v_pk_mul_f32 v[44:45], v[44:45], v[132:133]
	v_pk_mul_f32 v[40:41], v[40:41], v[136:137]
	v_pk_mul_f32 v[36:37], v[36:37], v[140:141]
	v_pk_mul_f32 v[46:47], v[46:47], v[78:79]
	v_pk_mul_f32 v[42:43], v[42:43], v[130:131]
	v_pk_mul_f32 v[38:39], v[38:39], v[134:135]
	v_pk_mul_f32 v[34:35], v[34:35], v[138:139]
	v_pk_mul_f32 v[32:33], v[32:33], v[80:81]
	v_pk_mul_f32 v[28:29], v[28:29], v[132:133]
	v_pk_mul_f32 v[24:25], v[24:25], v[136:137]
	v_pk_mul_f32 v[20:21], v[20:21], v[140:141]
	v_pk_mul_f32 v[30:31], v[30:31], v[78:79]
	v_pk_mul_f32 v[26:27], v[26:27], v[130:131]
	v_pk_mul_f32 v[22:23], v[22:23], v[134:135]
	v_pk_mul_f32 v[18:19], v[18:19], v[138:139]
